# attention causal skips extended: waves 4-5 skip the drain, waves 0-3 skip the key-score MFMAs of the second-to-last key tile
# speedup vs baseline: 1.0049x; 1.0008x over previous
.LBB0_432:
	s_lshl_b32 s4, s91, 1
	s_add_i32 s99, s97, 1
	s_cmp_eq_u32 s99, s90
	s_cselect_b32 s99, 1, 0
	s_cmp_lt_u32 s86, 4
	s_cselect_b32 s98, 1, 0
	s_and_b32 s99, s99, s98
	s_cmp_lg_u32 s99, 0
	v_add_u32_e32 v249, s4, v246
	ds_read_b64_tr_b16 v[214:215], v249 offset:24576
	ds_read_b64_tr_b16 v[216:217], v249 offset:25088
	s_cbranch_scc1 .Lq2_0
	v_mfma_f32_32x32x16_bf16 v[98:113], v[206:209], v[174:177], v[66:81]
.Lq2_0:
	v_add_f32_e32 v1, v130, v131
	v_add_f32_e32 v1, v132, v1
	v_add_f32_e32 v1, v133, v1
	v_add_f32_e32 v1, v134, v1
	v_add_f32_e32 v1, v135, v1
	v_cvt_pk_bf16_f32 v166, v130, v131
	v_cvt_pk_bf16_f32 v167, v132, v133
	ds_read_b64_tr_b16 v[218:219], v249 offset:28672
	ds_read_b64_tr_b16 v[220:221], v249 offset:29184
	s_cbranch_scc1 .Lq2_1
	v_mfma_f32_32x32x16_bf16 v[82:97], v[202:205], v[174:177], v[66:81]
.Lq2_1:
	v_add_f32_e32 v1, v136, v1
	v_add_f32_e32 v1, v137, v1
	v_add_f32_e32 v1, v138, v1
	v_add_f32_e32 v1, v139, v1
	v_cvt_pk_bf16_f32 v168, v134, v135
	v_cvt_pk_bf16_f32 v169, v136, v137
	ds_read_b64_tr_b16 v[210:211], v249 offset:25600
	ds_read_b64_tr_b16 v[212:213], v249 offset:26112
	s_cbranch_scc1 .Lq2_2
	v_mfma_f32_32x32x16_bf16 v[98:113], v[198:201], v[170:173], v[98:113]
.Lq2_2:
	v_add_f32_e32 v1, v140, v1
	v_add_f32_e32 v1, v141, v1
	v_add_f32_e32 v1, v142, v1
	v_add_f32_e32 v1, v143, v1
	v_cvt_pk_bf16_f32 v162, v138, v139
	v_cvt_pk_bf16_f32 v163, v140, v141
	ds_read_b64_tr_b16 v[134:135], v249 offset:29696
	ds_read_b64_tr_b16 v[136:137], v249 offset:30208
	s_cbranch_scc1 .Lq2_3
	v_mfma_f32_32x32x16_bf16 v[82:97], v[194:197], v[170:173], v[82:97]
.Lq2_3:
	v_add_f32_e32 v1, v144, v1
	v_add_f32_e32 v1, v145, v1
	v_add_f32_e32 v1, v114, v1
	v_add_f32_e32 v1, v115, v1
	v_cvt_pk_bf16_f32 v164, v142, v143
	v_cvt_pk_bf16_f32 v165, v144, v145
	ds_read_b64_tr_b16 v[130:131], v249 offset:26624
	ds_read_b64_tr_b16 v[132:133], v249 offset:27136
	s_cbranch_scc1 .Lq2_4
	v_mfma_f32_32x32x16_bf16 v[98:113], v[190:193], v[158:161], v[98:113]
.Lq2_4:
	v_add_f32_e32 v1, v116, v1
	v_add_f32_e32 v1, v117, v1
	v_add_f32_e32 v1, v118, v1
	v_add_f32_e32 v1, v119, v1
	v_cvt_pk_bf16_f32 v154, v114, v115
	v_cvt_pk_bf16_f32 v155, v116, v117
	ds_read_b64_tr_b16 v[114:115], v249 offset:30720
	ds_read_b64_tr_b16 v[116:117], v249 offset:31232
	s_cbranch_scc1 .Lq2_5
	v_mfma_f32_32x32x16_bf16 v[82:97], v[186:189], v[158:161], v[82:97]
.Lq2_5:
	v_add_f32_e32 v1, v120, v1
	v_add_f32_e32 v1, v121, v1
	v_add_f32_e32 v1, v122, v1
	v_add_f32_e32 v1, v123, v1
	v_cvt_pk_bf16_f32 v156, v118, v119
	v_cvt_pk_bf16_f32 v157, v120, v121
	ds_read_b64_tr_b16 v[118:119], v249 offset:27648
	ds_read_b64_tr_b16 v[120:121], v249 offset:28160
	s_cbranch_scc1 .Lq2_6
	v_mfma_f32_32x32x16_bf16 v[98:113], v[182:185], v[150:153], v[98:113]
.Lq2_6:
	v_add_f32_e32 v1, v124, v1
	v_add_f32_e32 v1, v125, v1
	v_add_f32_e32 v1, v126, v1
	v_add_f32_e32 v1, v127, v1
	v_cvt_pk_bf16_f32 v146, v122, v123
	v_cvt_pk_bf16_f32 v147, v124, v125
	ds_read_b64_tr_b16 v[122:123], v249 offset:31744
	ds_read_b64_tr_b16 v[124:125], v249 offset:32256
	s_cbranch_scc1 .Lq2_7
	v_mfma_f32_32x32x16_bf16 v[82:97], v[178:181], v[150:153], v[82:97]
.Lq2_7:
	v_add_f32_e32 v1, v128, v1
	v_add_f32_e32 v1, v129, v1
	v_add_f32_e32 v138, 0, v1
	v_cvt_pk_bf16_f32 v148, v126, v127
	v_cvt_pk_bf16_f32 v149, v128, v129
	s_add_i32 s93, s97, 2
	s_cmp_ge_i32 s93, s90
	s_cselect_b64 s[58:59], -1, 0
	s_and_b64 vcc, exec, s[58:59]
	s_cbranch_vccnz .LBB0_434
	s_add_i32 s4, s92, s88
	v_lshl_add_u64 v[126:127], v[230:231], 0, s[36:37]
	s_mov_b32 s5, m0
	s_mov_b32 m0, s4
	s_nop 0
	global_load_lds_dwordx4 v[126:127], off
	s_mov_b32 m0, s5

.LBB0_471:
	s_cmp_gt_u32 s86, 5
	s_cbranch_scc1 .Ldrain_go
	v_cmp_gt_u32_e32 vcc, 32, v234
	v_mov_b32_e32 v98, v114
	v_mov_b32_e32 v66, v114
	s_nop 1
	v_permlane32_swap_b32_e32 v98, v66
	s_and_saveexec_b64 s[4:5], vcc
	s_cbranch_execz .LBB0_386
	v_add_f32_e32 v1, v98, v66
	ds_write_b32 v240, v1 offset:128
	s_branch .LBB0_386
